# P0: the 8 per-row x loads issued together (were 8 serialized HBM round trips per row) with counted vmcnt(7) waits; on top of the micro-edit bundle
# speedup vs baseline: 1.0065x; 1.0026x over previous
.LBB0_16:
	s_cmp_lg_u64 s[20:21], 0
	v_mov_b32_e32 v2, 0
	s_cselect_b64 s[22:23], -1, 0
	s_cmp_eq_u64 s[20:21], 0
	v_mov_b32_e32 v6, 0
	v_mov_b32_e32 v7, 0
	v_mov_b32_e32 v8, 0
	v_mov_b32_e32 v9, 0
	s_cbranch_scc1 .LBB0_18
	global_load_dwordx4 v[60:63], v34, s[20:21] nt
	global_load_dwordx4 v[64:67], v34, s[20:21] offset:1024 nt
	global_load_dwordx4 v[68:71], v34, s[20:21] offset:2048 nt
	global_load_dwordx4 v[72:75], v34, s[20:21] offset:3072 nt
	v_lshlrev_b32_e32 v92, 2, v38
	global_load_dwordx4 v[76:79], v92, s[20:21] nt
	v_lshlrev_b32_e32 v93, 2, v40
	global_load_dwordx4 v[80:83], v93, s[20:21] nt
	v_lshlrev_b32_e32 v94, 2, v42
	global_load_dwordx4 v[84:87], v94, s[20:21] nt
	v_lshlrev_b32_e32 v95, 2, v44
	global_load_dwordx4 v[88:91], v95, s[20:21] nt
	s_waitcnt vmcnt(7)
	v_mov_b32_e32 v6, v60
	v_mov_b32_e32 v7, v61
	v_mov_b32_e32 v8, v62
	v_mov_b32_e32 v9, v63
.LBB0_18:
	v_bfe_u32 v3, v6, 16, 1
	v_add3_u32 v3, v6, v3, s26
	v_bfe_u32 v4, v7, 16, 1
	v_lshrrev_b32_e32 v3, 16, v3
	v_add3_u32 v4, v7, v4, s26
	s_ashr_i32 s13, s12, 31
	v_and_or_b32 v4, v4, s27, v3
	v_bfe_u32 v3, v8, 16, 1
	s_lshl_b64 s[6:7], s[12:13], 12
	v_add3_u32 v3, v8, v3, s26
	v_bfe_u32 v5, v9, 16, 1
	s_add_u32 s18, s80, s6
	v_lshrrev_b32_e32 v3, 16, v3
	v_add3_u32 v5, v9, v5, s26
	s_addc_u32 s19, s81, s7
	v_and_or_b32 v5, v5, s27, v3
	v_cndmask_b32_e64 v3, 0, 1, s[22:23]
	global_store_dwordx2 v47, v[4:5], s[18:19]
	v_cmp_ne_u32_e64 s[6:7], 1, v3
	s_andn2_b64 vcc, exec, s[22:23]
	v_mov_b32_e32 v3, 0
	v_mov_b32_e32 v4, 0
	v_mov_b32_e32 v5, 0
	s_cbranch_vccnz .LBB0_20
	s_waitcnt vmcnt(7)
	v_mov_b32_e32 v2, v64
	v_mov_b32_e32 v3, v65
	v_mov_b32_e32 v4, v66
	v_mov_b32_e32 v5, v67
.LBB0_20:
	v_bfe_u32 v10, v2, 16, 1
	v_add3_u32 v10, v2, v10, s26
	v_bfe_u32 v11, v3, 16, 1
	v_lshrrev_b32_e32 v10, 16, v10
	v_add3_u32 v11, v3, v11, s26
	v_and_or_b32 v10, v11, s27, v10
	v_bfe_u32 v11, v4, 16, 1
	v_add3_u32 v11, v4, v11, s26
	v_bfe_u32 v12, v5, 16, 1
	v_lshrrev_b32_e32 v11, 16, v11
	v_add3_u32 v12, v5, v12, s26
	v_and_or_b32 v11, v12, s27, v11
	global_store_dwordx2 v48, v[10:11], s[18:19]
	v_mov_b32_e32 v10, 0
	s_and_b64 vcc, exec, s[6:7]
	v_mov_b32_e32 v14, 0
	v_mov_b32_e32 v15, 0
	v_mov_b32_e32 v16, 0
	v_mov_b32_e32 v17, 0
	s_cbranch_vccnz .LBB0_22
	s_waitcnt vmcnt(7)
	v_mov_b32_e32 v14, v68
	v_mov_b32_e32 v15, v69
	v_mov_b32_e32 v16, v70
	v_mov_b32_e32 v17, v71
.LBB0_22:
	v_bfe_u32 v11, v14, 16, 1
	v_add3_u32 v11, v14, v11, s26
	v_bfe_u32 v12, v15, 16, 1
	v_lshrrev_b32_e32 v11, 16, v11
	v_add3_u32 v12, v15, v12, s26
	v_and_or_b32 v12, v12, s27, v11
	v_bfe_u32 v11, v16, 16, 1
	v_add3_u32 v11, v16, v11, s26
	v_bfe_u32 v13, v17, 16, 1
	v_lshrrev_b32_e32 v11, 16, v11
	v_add3_u32 v13, v17, v13, s26
	v_and_or_b32 v13, v13, s27, v11
	global_store_dwordx2 v49, v[12:13], s[18:19]
	s_and_b64 vcc, exec, s[6:7]
	v_mov_b32_e32 v11, 0
	v_mov_b32_e32 v12, 0
	v_mov_b32_e32 v13, 0
	s_cbranch_vccnz .LBB0_24
	s_waitcnt vmcnt(7)
	v_mov_b32_e32 v10, v72
	v_mov_b32_e32 v11, v73
	v_mov_b32_e32 v12, v74
	v_mov_b32_e32 v13, v75
.LBB0_24:
	v_bfe_u32 v18, v10, 16, 1
	v_add3_u32 v18, v10, v18, s26
	v_bfe_u32 v19, v11, 16, 1
	v_lshrrev_b32_e32 v18, 16, v18
	v_add3_u32 v19, v11, v19, s26
	v_and_or_b32 v18, v19, s27, v18
	v_bfe_u32 v19, v12, 16, 1
	v_add3_u32 v19, v12, v19, s26
	v_bfe_u32 v20, v13, 16, 1
	v_lshrrev_b32_e32 v19, 16, v19
	v_add3_u32 v20, v13, v20, s26
	v_and_or_b32 v19, v20, s27, v19
	global_store_dwordx2 v50, v[18:19], s[18:19]
	v_mov_b32_e32 v18, 0
	s_and_b64 vcc, exec, s[6:7]
	v_mov_b32_e32 v22, 0
	v_mov_b32_e32 v23, 0
	v_mov_b32_e32 v24, 0
	v_mov_b32_e32 v25, 0
	s_cbranch_vccnz .LBB0_26
	s_waitcnt vmcnt(7)
	v_mov_b32_e32 v22, v76
	v_mov_b32_e32 v23, v77
	v_mov_b32_e32 v24, v78
	v_mov_b32_e32 v25, v79
.LBB0_26:
	v_bfe_u32 v19, v22, 16, 1
	v_add3_u32 v19, v22, v19, s26
	v_bfe_u32 v20, v23, 16, 1
	v_lshrrev_b32_e32 v19, 16, v19
	v_add3_u32 v20, v23, v20, s26
	v_and_or_b32 v20, v20, s27, v19
	v_bfe_u32 v19, v24, 16, 1
	v_add3_u32 v19, v24, v19, s26
	v_bfe_u32 v21, v25, 16, 1
	v_lshrrev_b32_e32 v19, 16, v19
	v_add3_u32 v21, v25, v21, s26
	v_and_or_b32 v21, v21, s27, v19
	v_lshlrev_b32_e32 v19, 1, v38
	global_store_dwordx2 v19, v[20:21], s[18:19]
	s_and_b64 vcc, exec, s[6:7]
	v_mov_b32_e32 v19, 0
	v_mov_b32_e32 v20, 0
	v_mov_b32_e32 v21, 0
	s_cbranch_vccnz .LBB0_28
	s_waitcnt vmcnt(7)
	v_mov_b32_e32 v18, v80
	v_mov_b32_e32 v19, v81
	v_mov_b32_e32 v20, v82
	v_mov_b32_e32 v21, v83
.LBB0_28:
	v_bfe_u32 v26, v18, 16, 1
	v_add3_u32 v26, v18, v26, s26
	v_bfe_u32 v27, v19, 16, 1
	v_lshrrev_b32_e32 v26, 16, v26
	v_add3_u32 v27, v19, v27, s26
	v_and_or_b32 v26, v27, s27, v26
	v_bfe_u32 v27, v20, 16, 1
	v_add3_u32 v27, v20, v27, s26
	v_bfe_u32 v28, v21, 16, 1
	v_lshrrev_b32_e32 v27, 16, v27
	v_add3_u32 v28, v21, v28, s26
	v_and_or_b32 v27, v28, s27, v27
	v_lshlrev_b32_e32 v28, 1, v40
	global_store_dwordx2 v28, v[26:27], s[18:19]
	v_mov_b32_e32 v26, 0
	s_and_b64 vcc, exec, s[6:7]
	v_mov_b32_e32 v30, 0
	v_mov_b32_e32 v31, 0
	v_mov_b32_e32 v32, 0
	v_mov_b32_e32 v33, 0
	s_cbranch_vccnz .LBB0_30
	s_waitcnt vmcnt(7)
	v_mov_b32_e32 v30, v84
	v_mov_b32_e32 v31, v85
	v_mov_b32_e32 v32, v86
	v_mov_b32_e32 v33, v87
.LBB0_30:
	v_bfe_u32 v27, v30, 16, 1
	v_add3_u32 v27, v30, v27, s26
	v_bfe_u32 v28, v31, 16, 1
	v_lshrrev_b32_e32 v27, 16, v27
	v_add3_u32 v28, v31, v28, s26
	v_and_or_b32 v28, v28, s27, v27
	v_bfe_u32 v27, v32, 16, 1
	v_add3_u32 v27, v32, v27, s26
	v_bfe_u32 v29, v33, 16, 1
	v_lshrrev_b32_e32 v27, 16, v27
	v_add3_u32 v29, v33, v29, s26
	v_and_or_b32 v29, v29, s27, v27
	v_lshlrev_b32_e32 v27, 1, v42
	global_store_dwordx2 v27, v[28:29], s[18:19]
	s_and_b64 vcc, exec, s[6:7]
	v_mov_b32_e32 v27, 0
	v_mov_b32_e32 v28, 0
	v_mov_b32_e32 v29, 0
	s_cbranch_vccnz .LBB0_32
	s_waitcnt vmcnt(7)
	v_mov_b32_e32 v26, v88
	v_mov_b32_e32 v27, v89
	v_mov_b32_e32 v28, v90
	v_mov_b32_e32 v29, v91
.LBB0_32:
	v_mul_f32_e32 v3, v3, v3
	v_mul_f32_e32 v7, v7, v7
	v_fmac_f32_e32 v3, v2, v2
	v_mul_f32_e32 v2, v5, v5
	v_fmac_f32_e32 v7, v6, v6
	v_mul_f32_e32 v6, v9, v9
	v_fmac_f32_e32 v2, v4, v4
	v_fmac_f32_e32 v6, v8, v8
	v_add_f32_e32 v2, v3, v2
	v_mul_f32_e32 v3, v15, v15
	v_mul_f32_e32 v4, v17, v17
	v_add_f32_e32 v6, v7, v6
	v_fmac_f32_e32 v3, v14, v14
	v_fmac_f32_e32 v4, v16, v16
	v_add_f32_e32 v2, v6, v2
	v_add_f32_e32 v3, v3, v4
	v_add_f32_e32 v2, v2, v3
	v_mul_f32_e32 v3, v11, v11
	v_mul_f32_e32 v4, v13, v13
	v_fmac_f32_e32 v3, v10, v10
	v_fmac_f32_e32 v4, v12, v12
	v_add_f32_e32 v3, v3, v4
	v_add_f32_e32 v2, v2, v3
	v_mul_f32_e32 v3, v23, v23
	v_mul_f32_e32 v4, v25, v25
	v_fmac_f32_e32 v3, v22, v22
	v_fmac_f32_e32 v4, v24, v24
	v_add_f32_e32 v3, v3, v4
	v_add_f32_e32 v2, v2, v3
	v_mul_f32_e32 v3, v19, v19
	v_mul_f32_e32 v4, v21, v21
	v_fmac_f32_e32 v3, v18, v18
	v_fmac_f32_e32 v4, v20, v20
	v_add_f32_e32 v3, v3, v4
	v_add_f32_e32 v2, v2, v3
	v_mul_f32_e32 v3, v31, v31
	v_mul_f32_e32 v4, v33, v33
	v_fmac_f32_e32 v3, v30, v30
	v_fmac_f32_e32 v4, v32, v32
	v_add_f32_e32 v3, v3, v4
	v_add_f32_e32 v2, v2, v3
	v_mul_f32_e32 v3, v27, v27
	v_mul_f32_e32 v4, v29, v29
	v_fmac_f32_e32 v3, v26, v26
	v_fmac_f32_e32 v4, v28, v28
	v_add_f32_e32 v3, v3, v4
	v_add_f32_e32 v2, v2, v3
	ds_bpermute_b32 v3, v1, v2
	v_bfe_u32 v4, v26, 16, 1
	v_add3_u32 v4, v26, v4, s26
	v_bfe_u32 v6, v29, 16, 1
	s_waitcnt lgkmcnt(0)
	v_add_f32_e32 v2, v2, v3
	ds_bpermute_b32 v3, v39, v2
	s_waitcnt lgkmcnt(0)
	v_add_f32_e32 v2, v2, v3
	ds_bpermute_b32 v3, v41, v2
	s_waitcnt lgkmcnt(0)
	v_add_f32_e32 v3, v2, v3
	ds_bpermute_b32 v5, v43, v3
	v_lshrrev_b32_e32 v2, 16, v4
	v_bfe_u32 v4, v27, 16, 1
	v_add3_u32 v4, v27, v4, s26
	v_and_or_b32 v2, v4, s27, v2
	s_waitcnt lgkmcnt(0)
	v_add_f32_e32 v3, v3, v5
	ds_bpermute_b32 v4, v45, v3
	v_bfe_u32 v5, v28, 16, 1
	v_add3_u32 v5, v28, v5, s26
	v_lshrrev_b32_e32 v5, 16, v5
	s_waitcnt lgkmcnt(0)
	v_add_f32_e32 v4, v3, v4
	ds_bpermute_b32 v7, v46, v4
	v_add3_u32 v3, v29, v6, s26
	v_and_or_b32 v3, v3, s27, v5
	v_lshlrev_b32_e32 v5, 1, v44
	global_store_dwordx2 v5, v[2:3], s[18:19]
	s_waitcnt lgkmcnt(0)
	v_add_f32_e32 v2, v4, v7
	s_and_saveexec_b64 s[6:7], s[8:9]
	s_cbranch_execnz .LBB0_34
	s_or_b64 exec, exec, s[6:7]
	s_and_saveexec_b64 s[6:7], s[4:5]
	s_cbranch_execz .LBB0_10
	s_branch .LBB0_35
